# EpiConv: the two channel quads of a lane packed into one dwordx4 store per row group (16 stores of 64 B per row instead of 32 of 2x8 B)
# speedup vs baseline: 1.0134x; 1.0134x over previous
.LBB0_1187:
	v_readlane_b32 s12, v253, 21
	v_readlane_b32 s13, v253, 22
	v_readlane_b32 s18, v253, 27
	v_readlane_b32 s19, v253, 28
	v_readlane_b32 s20, v253, 29
	v_readlane_b32 s21, v253, 30
	v_readlane_b32 s22, v253, 31
	v_readlane_b32 s23, v253, 32
	v_readlane_b32 s24, v253, 33
	v_readlane_b32 s25, v253, 34
	v_readlane_b32 s26, v253, 35
	v_readlane_b32 s27, v253, 36
	s_mov_b64 s[14:15], s[2:3]
	s_mov_b64 s[16:17], s[34:35]
	v_lshl_or_b32 v176, s66, 7, v220
	v_lshlrev_b32_e32 v208, 2, v176
	s_lshl_b32 s34, s64, 8
	s_add_i32 s34, s34, s67
	s_lshr_b32 s35, s34, 4
	v_add_u32_e32 v209, s35, v217
	v_mul_u32_u24_e32 v209, 0x5800, v209
	v_add_u32_e32 v209, v209, v208
	v_or_b32_e32 v210, s34, v217
	v_mul_u32_u24_e32 v210, 0x1600, v210
	v_lshl_add_u32 v210, v176, 1, v210
	global_load_dwordx4 v[112:115], v208, s[24:25]
	global_load_dwordx4 v[116:119], v208, s[16:17]
	global_load_dwordx4 v[120:123], v208, s[30:31]
	global_load_dwordx4 v[124:127], v208, s[26:27]
	global_load_dwordx4 v[132:135], v208, s[14:15]
	global_load_dwordx4 v[136:139], v208, s[28:29]
	global_load_dwordx4 v[140:143], v208, s[40:41]
	global_load_dwordx4 v[144:147], v208, s[44:45]
	global_load_dwordx4 v[176:179], v208, s[24:25] offset:16
	global_load_dwordx4 v[180:183], v208, s[16:17] offset:16
	global_load_dwordx4 v[184:187], v208, s[30:31] offset:16
	global_load_dwordx4 v[188:191], v208, s[26:27] offset:16
	global_load_dwordx4 v[192:195], v208, s[14:15] offset:16
	global_load_dwordx4 v[196:199], v208, s[28:29] offset:16
	global_load_dwordx4 v[200:203], v208, s[40:41] offset:16
	global_load_dwordx4 v[204:207], v208, s[44:45] offset:16
	s_and_saveexec_b64 s[2:3], s[6:7]
	global_store_dwordx4 v209, v[156:159], s[38:39]
	global_store_dwordx4 v209, v[60:63], s[38:39] offset:16
	v_add_u32_e32 v211, 0x2c00, v209
	global_store_dwordx4 v211, v[152:155], s[38:39]
	global_store_dwordx4 v211, v[56:59], s[38:39] offset:16
	v_add_u32_e32 v211, 0x2c000, v209
	global_store_dwordx4 v211, v[92:95], s[38:39]
	global_store_dwordx4 v211, v[28:31], s[38:39] offset:16
	v_add_u32_e32 v211, 0x2ec00, v209
	global_store_dwordx4 v211, v[88:91], s[38:39]
	global_store_dwordx4 v211, v[24:27], s[38:39] offset:16
	s_or_b64 exec, exec, s[2:3]
	v_add_u32_e32 v212, 0xfffbe000, v209
	s_and_saveexec_b64 s[2:3], s[8:9]
	global_store_dwordx4 v212, v[100:103], s[38:39]
	global_store_dwordx4 v212, v[36:39], s[38:39] offset:16
	v_add_u32_e32 v211, 0x2c00, v212
	global_store_dwordx4 v211, v[96:99], s[38:39]
	global_store_dwordx4 v211, v[32:35], s[38:39] offset:16
	v_add_u32_e32 v211, 0x2c000, v212
	global_store_dwordx4 v211, v[68:71], s[38:39]
	global_store_dwordx4 v211, v[4:7], s[38:39] offset:16
	v_add_u32_e32 v211, 0x2ec00, v212
	global_store_dwordx4 v211, v[64:67], s[38:39]
	global_store_dwordx4 v211, v[0:3], s[38:39] offset:16
	s_or_b64 exec, exec, s[2:3]
	v_mov_b32_e32 v238, 0xbfb8aa3b
	v_mov_b32_e32 v239, 0xbfb8aa3b
	s_waitcnt vmcnt(16)
	v_pk_fma_f32 v[224:225], v[116:117], v[156:157], v[124:125]
	v_pk_fma_f32 v[226:227], v[118:119], v[158:159], v[126:127]
	v_fmac_f32_dpp v224, v156, v112 row_shr:1 row_mask:0xf bank_mask:0xf
	v_fmac_f32_dpp v225, v157, v113 row_shr:1 row_mask:0xf bank_mask:0xf
	v_fmac_f32_dpp v226, v158, v114 row_shr:1 row_mask:0xf bank_mask:0xf
	v_fmac_f32_dpp v227, v159, v115 row_shr:1 row_mask:0xf bank_mask:0xf
	v_fmac_f32_dpp v224, v156, v120 row_shl:1 row_mask:0xf bank_mask:0xf
	v_fmac_f32_dpp v225, v157, v121 row_shl:1 row_mask:0xf bank_mask:0xf
	v_fmac_f32_dpp v226, v158, v122 row_shl:1 row_mask:0xf bank_mask:0xf
	v_fmac_f32_dpp v227, v159, v123 row_shl:1 row_mask:0xf bank_mask:0xf
	v_fmac_f32_dpp v224, v148, v120 row_shr:15 row_mask:0xf bank_mask:0xf
	v_fmac_f32_dpp v225, v149, v121 row_shr:15 row_mask:0xf bank_mask:0xf
	v_fmac_f32_dpp v226, v150, v122 row_shr:15 row_mask:0xf bank_mask:0xf
	v_fmac_f32_dpp v227, v151, v123 row_shr:15 row_mask:0xf bank_mask:0xf
	v_pk_fma_f32 v[228:229], v[136:137], v[152:153], v[144:145]
	v_pk_fma_f32 v[230:231], v[138:139], v[154:155], v[146:147]
	v_fmac_f32_dpp v228, v152, v132 row_shr:1 row_mask:0xf bank_mask:0xf
	v_fmac_f32_dpp v229, v153, v133 row_shr:1 row_mask:0xf bank_mask:0xf
	v_fmac_f32_dpp v230, v154, v134 row_shr:1 row_mask:0xf bank_mask:0xf
	v_fmac_f32_dpp v231, v155, v135 row_shr:1 row_mask:0xf bank_mask:0xf
	v_fmac_f32_dpp v228, v152, v140 row_shl:1 row_mask:0xf bank_mask:0xf
	v_fmac_f32_dpp v229, v153, v141 row_shl:1 row_mask:0xf bank_mask:0xf
	v_fmac_f32_dpp v230, v154, v142 row_shl:1 row_mask:0xf bank_mask:0xf
	v_fmac_f32_dpp v231, v155, v143 row_shl:1 row_mask:0xf bank_mask:0xf
	v_fmac_f32_dpp v228, v128, v140 row_shr:15 row_mask:0xf bank_mask:0xf
	v_fmac_f32_dpp v229, v129, v141 row_shr:15 row_mask:0xf bank_mask:0xf
	v_fmac_f32_dpp v230, v130, v142 row_shr:15 row_mask:0xf bank_mask:0xf
	v_fmac_f32_dpp v231, v131, v143 row_shr:15 row_mask:0xf bank_mask:0xf
	v_pk_mul_f32 v[232:233], v[224:225], v[238:239]
	v_pk_mul_f32 v[234:235], v[226:227], v[238:239]
	v_exp_f32_e32 v232, v232
	v_exp_f32_e32 v233, v233
	v_exp_f32_e32 v234, v234
	v_exp_f32_e32 v235, v235
	v_pk_add_f32 v[232:233], v[232:233], 1.0 op_sel_hi:[1,0]
	v_pk_add_f32 v[234:235], v[234:235], 1.0 op_sel_hi:[1,0]
	v_rcp_f32_e32 v232, v232
	v_rcp_f32_e32 v233, v233
	v_rcp_f32_e32 v234, v234
	v_rcp_f32_e32 v235, v235
	v_pk_mul_f32 v[224:225], v[224:225], v[232:233]
	v_pk_mul_f32 v[226:227], v[226:227], v[234:235]
	v_pk_mul_f32 v[224:225], v[224:225], v[228:229]
	v_pk_mul_f32 v[226:227], v[226:227], v[230:231]
	v_cvt_pk_bf16_f32 v244, v224, v225
	v_cvt_pk_bf16_f32 v245, v226, v227
	v_pk_fma_f32 v[224:225], v[180:181], v[60:61], v[188:189]
	v_pk_fma_f32 v[226:227], v[182:183], v[62:63], v[190:191]
	v_fmac_f32_dpp v224, v60, v176 row_shr:1 row_mask:0xf bank_mask:0xf
	v_fmac_f32_dpp v225, v61, v177 row_shr:1 row_mask:0xf bank_mask:0xf
	v_fmac_f32_dpp v226, v62, v178 row_shr:1 row_mask:0xf bank_mask:0xf
	v_fmac_f32_dpp v227, v63, v179 row_shr:1 row_mask:0xf bank_mask:0xf
	v_fmac_f32_dpp v224, v60, v184 row_shl:1 row_mask:0xf bank_mask:0xf
	v_fmac_f32_dpp v225, v61, v185 row_shl:1 row_mask:0xf bank_mask:0xf
	v_fmac_f32_dpp v226, v62, v186 row_shl:1 row_mask:0xf bank_mask:0xf
	v_fmac_f32_dpp v227, v63, v187 row_shl:1 row_mask:0xf bank_mask:0xf
	v_fmac_f32_dpp v224, v52, v184 row_shr:15 row_mask:0xf bank_mask:0xf
	v_fmac_f32_dpp v225, v53, v185 row_shr:15 row_mask:0xf bank_mask:0xf
	v_fmac_f32_dpp v226, v54, v186 row_shr:15 row_mask:0xf bank_mask:0xf
	v_fmac_f32_dpp v227, v55, v187 row_shr:15 row_mask:0xf bank_mask:0xf
	v_pk_fma_f32 v[228:229], v[196:197], v[56:57], v[204:205]
	v_pk_fma_f32 v[230:231], v[198:199], v[58:59], v[206:207]
	v_fmac_f32_dpp v228, v56, v192 row_shr:1 row_mask:0xf bank_mask:0xf
	v_fmac_f32_dpp v229, v57, v193 row_shr:1 row_mask:0xf bank_mask:0xf
	v_fmac_f32_dpp v230, v58, v194 row_shr:1 row_mask:0xf bank_mask:0xf
	v_fmac_f32_dpp v231, v59, v195 row_shr:1 row_mask:0xf bank_mask:0xf
	v_fmac_f32_dpp v228, v56, v200 row_shl:1 row_mask:0xf bank_mask:0xf
	v_fmac_f32_dpp v229, v57, v201 row_shl:1 row_mask:0xf bank_mask:0xf
	v_fmac_f32_dpp v230, v58, v202 row_shl:1 row_mask:0xf bank_mask:0xf
	v_fmac_f32_dpp v231, v59, v203 row_shl:1 row_mask:0xf bank_mask:0xf
	v_fmac_f32_dpp v228, v48, v200 row_shr:15 row_mask:0xf bank_mask:0xf
	v_fmac_f32_dpp v229, v49, v201 row_shr:15 row_mask:0xf bank_mask:0xf
	v_fmac_f32_dpp v230, v50, v202 row_shr:15 row_mask:0xf bank_mask:0xf
	v_fmac_f32_dpp v231, v51, v203 row_shr:15 row_mask:0xf bank_mask:0xf
	v_pk_mul_f32 v[232:233], v[224:225], v[238:239]
	v_pk_mul_f32 v[234:235], v[226:227], v[238:239]
	v_exp_f32_e32 v232, v232
	v_exp_f32_e32 v233, v233
	v_exp_f32_e32 v234, v234
	v_exp_f32_e32 v235, v235
	v_pk_add_f32 v[232:233], v[232:233], 1.0 op_sel_hi:[1,0]
	v_pk_add_f32 v[234:235], v[234:235], 1.0 op_sel_hi:[1,0]
	v_rcp_f32_e32 v232, v232
	v_rcp_f32_e32 v233, v233
	v_rcp_f32_e32 v234, v234
	v_rcp_f32_e32 v235, v235
	v_pk_mul_f32 v[224:225], v[224:225], v[232:233]
	v_pk_mul_f32 v[226:227], v[226:227], v[234:235]
	v_pk_mul_f32 v[224:225], v[224:225], v[228:229]
	v_pk_mul_f32 v[226:227], v[226:227], v[230:231]
	v_cvt_pk_bf16_f32 v246, v224, v225
	v_cvt_pk_bf16_f32 v247, v226, v227
	global_store_dwordx4 v210, v[244:247], s[36:37]
	v_pk_fma_f32 v[224:225], v[116:117], v[148:149], v[124:125]
	v_pk_fma_f32 v[226:227], v[118:119], v[150:151], v[126:127]
	v_fmac_f32_dpp v224, v148, v112 row_shr:1 row_mask:0xf bank_mask:0xf
	v_fmac_f32_dpp v225, v149, v113 row_shr:1 row_mask:0xf bank_mask:0xf
	v_fmac_f32_dpp v226, v150, v114 row_shr:1 row_mask:0xf bank_mask:0xf
	v_fmac_f32_dpp v227, v151, v115 row_shr:1 row_mask:0xf bank_mask:0xf
	v_fmac_f32_dpp v224, v156, v112 row_shl:15 row_mask:0xf bank_mask:0xf
	v_fmac_f32_dpp v225, v157, v113 row_shl:15 row_mask:0xf bank_mask:0xf
	v_fmac_f32_dpp v226, v158, v114 row_shl:15 row_mask:0xf bank_mask:0xf
	v_fmac_f32_dpp v227, v159, v115 row_shl:15 row_mask:0xf bank_mask:0xf
	v_fmac_f32_dpp v224, v148, v120 row_shl:1 row_mask:0xf bank_mask:0xf
	v_fmac_f32_dpp v225, v149, v121 row_shl:1 row_mask:0xf bank_mask:0xf
	v_fmac_f32_dpp v226, v150, v122 row_shl:1 row_mask:0xf bank_mask:0xf
	v_fmac_f32_dpp v227, v151, v123 row_shl:1 row_mask:0xf bank_mask:0xf
	v_fmac_f32_dpp v224, v108, v120 row_shr:15 row_mask:0xf bank_mask:0xf
	v_fmac_f32_dpp v225, v109, v121 row_shr:15 row_mask:0xf bank_mask:0xf
	v_fmac_f32_dpp v226, v110, v122 row_shr:15 row_mask:0xf bank_mask:0xf
	v_fmac_f32_dpp v227, v111, v123 row_shr:15 row_mask:0xf bank_mask:0xf
	v_pk_fma_f32 v[228:229], v[136:137], v[128:129], v[144:145]
	v_pk_fma_f32 v[230:231], v[138:139], v[130:131], v[146:147]
	v_fmac_f32_dpp v228, v128, v132 row_shr:1 row_mask:0xf bank_mask:0xf
	v_fmac_f32_dpp v229, v129, v133 row_shr:1 row_mask:0xf bank_mask:0xf
	v_fmac_f32_dpp v230, v130, v134 row_shr:1 row_mask:0xf bank_mask:0xf
	v_fmac_f32_dpp v231, v131, v135 row_shr:1 row_mask:0xf bank_mask:0xf
	v_fmac_f32_dpp v228, v152, v132 row_shl:15 row_mask:0xf bank_mask:0xf
	v_fmac_f32_dpp v229, v153, v133 row_shl:15 row_mask:0xf bank_mask:0xf
	v_fmac_f32_dpp v230, v154, v134 row_shl:15 row_mask:0xf bank_mask:0xf
	v_fmac_f32_dpp v231, v155, v135 row_shl:15 row_mask:0xf bank_mask:0xf
	v_fmac_f32_dpp v228, v128, v140 row_shl:1 row_mask:0xf bank_mask:0xf
	v_fmac_f32_dpp v229, v129, v141 row_shl:1 row_mask:0xf bank_mask:0xf
	v_fmac_f32_dpp v230, v130, v142 row_shl:1 row_mask:0xf bank_mask:0xf
	v_fmac_f32_dpp v231, v131, v143 row_shl:1 row_mask:0xf bank_mask:0xf
	v_fmac_f32_dpp v228, v104, v140 row_shr:15 row_mask:0xf bank_mask:0xf
	v_fmac_f32_dpp v229, v105, v141 row_shr:15 row_mask:0xf bank_mask:0xf
	v_fmac_f32_dpp v230, v106, v142 row_shr:15 row_mask:0xf bank_mask:0xf
	v_fmac_f32_dpp v231, v107, v143 row_shr:15 row_mask:0xf bank_mask:0xf
	v_pk_mul_f32 v[232:233], v[224:225], v[238:239]
	v_pk_mul_f32 v[234:235], v[226:227], v[238:239]
	v_exp_f32_e32 v232, v232
	v_exp_f32_e32 v233, v233
	v_exp_f32_e32 v234, v234
	v_exp_f32_e32 v235, v235
	v_pk_add_f32 v[232:233], v[232:233], 1.0 op_sel_hi:[1,0]
	v_pk_add_f32 v[234:235], v[234:235], 1.0 op_sel_hi:[1,0]
	v_rcp_f32_e32 v232, v232
	v_rcp_f32_e32 v233, v233
	v_rcp_f32_e32 v234, v234
	v_rcp_f32_e32 v235, v235
	v_pk_mul_f32 v[224:225], v[224:225], v[232:233]
	v_pk_mul_f32 v[226:227], v[226:227], v[234:235]
	v_pk_mul_f32 v[224:225], v[224:225], v[228:229]
	v_pk_mul_f32 v[226:227], v[226:227], v[230:231]
	v_cvt_pk_bf16_f32 v244, v224, v225
	v_cvt_pk_bf16_f32 v245, v226, v227
	v_pk_fma_f32 v[224:225], v[180:181], v[52:53], v[188:189]
	v_pk_fma_f32 v[226:227], v[182:183], v[54:55], v[190:191]
	v_fmac_f32_dpp v224, v52, v176 row_shr:1 row_mask:0xf bank_mask:0xf
	v_fmac_f32_dpp v225, v53, v177 row_shr:1 row_mask:0xf bank_mask:0xf
	v_fmac_f32_dpp v226, v54, v178 row_shr:1 row_mask:0xf bank_mask:0xf
	v_fmac_f32_dpp v227, v55, v179 row_shr:1 row_mask:0xf bank_mask:0xf
	v_fmac_f32_dpp v224, v60, v176 row_shl:15 row_mask:0xf bank_mask:0xf
	v_fmac_f32_dpp v225, v61, v177 row_shl:15 row_mask:0xf bank_mask:0xf
	v_fmac_f32_dpp v226, v62, v178 row_shl:15 row_mask:0xf bank_mask:0xf
	v_fmac_f32_dpp v227, v63, v179 row_shl:15 row_mask:0xf bank_mask:0xf
	v_fmac_f32_dpp v224, v52, v184 row_shl:1 row_mask:0xf bank_mask:0xf
	v_fmac_f32_dpp v225, v53, v185 row_shl:1 row_mask:0xf bank_mask:0xf
	v_fmac_f32_dpp v226, v54, v186 row_shl:1 row_mask:0xf bank_mask:0xf
	v_fmac_f32_dpp v227, v55, v187 row_shl:1 row_mask:0xf bank_mask:0xf
	v_fmac_f32_dpp v224, v44, v184 row_shr:15 row_mask:0xf bank_mask:0xf
	v_fmac_f32_dpp v225, v45, v185 row_shr:15 row_mask:0xf bank_mask:0xf
	v_fmac_f32_dpp v226, v46, v186 row_shr:15 row_mask:0xf bank_mask:0xf
	v_fmac_f32_dpp v227, v47, v187 row_shr:15 row_mask:0xf bank_mask:0xf
	v_pk_fma_f32 v[228:229], v[196:197], v[48:49], v[204:205]
	v_pk_fma_f32 v[230:231], v[198:199], v[50:51], v[206:207]
	v_fmac_f32_dpp v228, v48, v192 row_shr:1 row_mask:0xf bank_mask:0xf
	v_fmac_f32_dpp v229, v49, v193 row_shr:1 row_mask:0xf bank_mask:0xf
	v_fmac_f32_dpp v230, v50, v194 row_shr:1 row_mask:0xf bank_mask:0xf
	v_fmac_f32_dpp v231, v51, v195 row_shr:1 row_mask:0xf bank_mask:0xf
	v_fmac_f32_dpp v228, v56, v192 row_shl:15 row_mask:0xf bank_mask:0xf
	v_fmac_f32_dpp v229, v57, v193 row_shl:15 row_mask:0xf bank_mask:0xf
	v_fmac_f32_dpp v230, v58, v194 row_shl:15 row_mask:0xf bank_mask:0xf
	v_fmac_f32_dpp v231, v59, v195 row_shl:15 row_mask:0xf bank_mask:0xf
	v_fmac_f32_dpp v228, v48, v200 row_shl:1 row_mask:0xf bank_mask:0xf
	v_fmac_f32_dpp v229, v49, v201 row_shl:1 row_mask:0xf bank_mask:0xf
	v_fmac_f32_dpp v230, v50, v202 row_shl:1 row_mask:0xf bank_mask:0xf
	v_fmac_f32_dpp v231, v51, v203 row_shl:1 row_mask:0xf bank_mask:0xf
	v_fmac_f32_dpp v228, v40, v200 row_shr:15 row_mask:0xf bank_mask:0xf
	v_fmac_f32_dpp v229, v41, v201 row_shr:15 row_mask:0xf bank_mask:0xf
	v_fmac_f32_dpp v230, v42, v202 row_shr:15 row_mask:0xf bank_mask:0xf
	v_fmac_f32_dpp v231, v43, v203 row_shr:15 row_mask:0xf bank_mask:0xf
	v_pk_mul_f32 v[232:233], v[224:225], v[238:239]
	v_pk_mul_f32 v[234:235], v[226:227], v[238:239]
	v_exp_f32_e32 v232, v232
	v_exp_f32_e32 v233, v233
	v_exp_f32_e32 v234, v234
	v_exp_f32_e32 v235, v235
	v_pk_add_f32 v[232:233], v[232:233], 1.0 op_sel_hi:[1,0]
	v_pk_add_f32 v[234:235], v[234:235], 1.0 op_sel_hi:[1,0]
	v_rcp_f32_e32 v232, v232
	v_rcp_f32_e32 v233, v233
	v_rcp_f32_e32 v234, v234
	v_rcp_f32_e32 v235, v235
	v_pk_mul_f32 v[224:225], v[224:225], v[232:233]
	v_pk_mul_f32 v[226:227], v[226:227], v[234:235]
	v_pk_mul_f32 v[224:225], v[224:225], v[228:229]
	v_pk_mul_f32 v[226:227], v[226:227], v[230:231]
	v_cvt_pk_bf16_f32 v246, v224, v225
	v_cvt_pk_bf16_f32 v247, v226, v227
	v_add_u32_e32 v213, 0x16000, v210
	global_store_dwordx4 v213, v[244:247], s[36:37]
	v_pk_fma_f32 v[224:225], v[116:117], v[108:109], v[124:125]
	v_pk_fma_f32 v[226:227], v[118:119], v[110:111], v[126:127]
	v_fmac_f32_dpp v224, v108, v112 row_shr:1 row_mask:0xf bank_mask:0xf
	v_fmac_f32_dpp v225, v109, v113 row_shr:1 row_mask:0xf bank_mask:0xf
	v_fmac_f32_dpp v226, v110, v114 row_shr:1 row_mask:0xf bank_mask:0xf
	v_fmac_f32_dpp v227, v111, v115 row_shr:1 row_mask:0xf bank_mask:0xf
	v_fmac_f32_dpp v224, v148, v112 row_shl:15 row_mask:0xf bank_mask:0xf
	v_fmac_f32_dpp v225, v149, v113 row_shl:15 row_mask:0xf bank_mask:0xf
	v_fmac_f32_dpp v226, v150, v114 row_shl:15 row_mask:0xf bank_mask:0xf
	v_fmac_f32_dpp v227, v151, v115 row_shl:15 row_mask:0xf bank_mask:0xf
	v_fmac_f32_dpp v224, v108, v120 row_shl:1 row_mask:0xf bank_mask:0xf
	v_fmac_f32_dpp v225, v109, v121 row_shl:1 row_mask:0xf bank_mask:0xf
	v_fmac_f32_dpp v226, v110, v122 row_shl:1 row_mask:0xf bank_mask:0xf
	v_fmac_f32_dpp v227, v111, v123 row_shl:1 row_mask:0xf bank_mask:0xf
	v_fmac_f32_dpp v224, v100, v120 row_shr:15 row_mask:0xf bank_mask:0xf
	v_fmac_f32_dpp v225, v101, v121 row_shr:15 row_mask:0xf bank_mask:0xf
	v_fmac_f32_dpp v226, v102, v122 row_shr:15 row_mask:0xf bank_mask:0xf
	v_fmac_f32_dpp v227, v103, v123 row_shr:15 row_mask:0xf bank_mask:0xf
	v_pk_fma_f32 v[228:229], v[136:137], v[104:105], v[144:145]
	v_pk_fma_f32 v[230:231], v[138:139], v[106:107], v[146:147]
	v_fmac_f32_dpp v228, v104, v132 row_shr:1 row_mask:0xf bank_mask:0xf
	v_fmac_f32_dpp v229, v105, v133 row_shr:1 row_mask:0xf bank_mask:0xf
	v_fmac_f32_dpp v230, v106, v134 row_shr:1 row_mask:0xf bank_mask:0xf
	v_fmac_f32_dpp v231, v107, v135 row_shr:1 row_mask:0xf bank_mask:0xf
	v_fmac_f32_dpp v228, v128, v132 row_shl:15 row_mask:0xf bank_mask:0xf
	v_fmac_f32_dpp v229, v129, v133 row_shl:15 row_mask:0xf bank_mask:0xf
	v_fmac_f32_dpp v230, v130, v134 row_shl:15 row_mask:0xf bank_mask:0xf
	v_fmac_f32_dpp v231, v131, v135 row_shl:15 row_mask:0xf bank_mask:0xf
	v_fmac_f32_dpp v228, v104, v140 row_shl:1 row_mask:0xf bank_mask:0xf
	v_fmac_f32_dpp v229, v105, v141 row_shl:1 row_mask:0xf bank_mask:0xf
	v_fmac_f32_dpp v230, v106, v142 row_shl:1 row_mask:0xf bank_mask:0xf
	v_fmac_f32_dpp v231, v107, v143 row_shl:1 row_mask:0xf bank_mask:0xf
	v_fmac_f32_dpp v228, v96, v140 row_shr:15 row_mask:0xf bank_mask:0xf
	v_fmac_f32_dpp v229, v97, v141 row_shr:15 row_mask:0xf bank_mask:0xf
	v_fmac_f32_dpp v230, v98, v142 row_shr:15 row_mask:0xf bank_mask:0xf
	v_fmac_f32_dpp v231, v99, v143 row_shr:15 row_mask:0xf bank_mask:0xf
	v_pk_mul_f32 v[232:233], v[224:225], v[238:239]
	v_pk_mul_f32 v[234:235], v[226:227], v[238:239]
	v_exp_f32_e32 v232, v232
	v_exp_f32_e32 v233, v233
	v_exp_f32_e32 v234, v234
	v_exp_f32_e32 v235, v235
	v_pk_add_f32 v[232:233], v[232:233], 1.0 op_sel_hi:[1,0]
	v_pk_add_f32 v[234:235], v[234:235], 1.0 op_sel_hi:[1,0]
	v_rcp_f32_e32 v232, v232
	v_rcp_f32_e32 v233, v233
	v_rcp_f32_e32 v234, v234
	v_rcp_f32_e32 v235, v235
	v_pk_mul_f32 v[224:225], v[224:225], v[232:233]
	v_pk_mul_f32 v[226:227], v[226:227], v[234:235]
	v_pk_mul_f32 v[224:225], v[224:225], v[228:229]
	v_pk_mul_f32 v[226:227], v[226:227], v[230:231]
	v_cvt_pk_bf16_f32 v244, v224, v225
	v_cvt_pk_bf16_f32 v245, v226, v227
	v_pk_fma_f32 v[224:225], v[180:181], v[44:45], v[188:189]
	v_pk_fma_f32 v[226:227], v[182:183], v[46:47], v[190:191]
	v_fmac_f32_dpp v224, v44, v176 row_shr:1 row_mask:0xf bank_mask:0xf
	v_fmac_f32_dpp v225, v45, v177 row_shr:1 row_mask:0xf bank_mask:0xf
	v_fmac_f32_dpp v226, v46, v178 row_shr:1 row_mask:0xf bank_mask:0xf
	v_fmac_f32_dpp v227, v47, v179 row_shr:1 row_mask:0xf bank_mask:0xf
	v_fmac_f32_dpp v224, v52, v176 row_shl:15 row_mask:0xf bank_mask:0xf
	v_fmac_f32_dpp v225, v53, v177 row_shl:15 row_mask:0xf bank_mask:0xf
	v_fmac_f32_dpp v226, v54, v178 row_shl:15 row_mask:0xf bank_mask:0xf
	v_fmac_f32_dpp v227, v55, v179 row_shl:15 row_mask:0xf bank_mask:0xf
	v_fmac_f32_dpp v224, v44, v184 row_shl:1 row_mask:0xf bank_mask:0xf
	v_fmac_f32_dpp v225, v45, v185 row_shl:1 row_mask:0xf bank_mask:0xf
	v_fmac_f32_dpp v226, v46, v186 row_shl:1 row_mask:0xf bank_mask:0xf
	v_fmac_f32_dpp v227, v47, v187 row_shl:1 row_mask:0xf bank_mask:0xf
	v_fmac_f32_dpp v224, v36, v184 row_shr:15 row_mask:0xf bank_mask:0xf
	v_fmac_f32_dpp v225, v37, v185 row_shr:15 row_mask:0xf bank_mask:0xf
	v_fmac_f32_dpp v226, v38, v186 row_shr:15 row_mask:0xf bank_mask:0xf
	v_fmac_f32_dpp v227, v39, v187 row_shr:15 row_mask:0xf bank_mask:0xf
	v_pk_fma_f32 v[228:229], v[196:197], v[40:41], v[204:205]
	v_pk_fma_f32 v[230:231], v[198:199], v[42:43], v[206:207]
	v_fmac_f32_dpp v228, v40, v192 row_shr:1 row_mask:0xf bank_mask:0xf
	v_fmac_f32_dpp v229, v41, v193 row_shr:1 row_mask:0xf bank_mask:0xf
	v_fmac_f32_dpp v230, v42, v194 row_shr:1 row_mask:0xf bank_mask:0xf
	v_fmac_f32_dpp v231, v43, v195 row_shr:1 row_mask:0xf bank_mask:0xf
	v_fmac_f32_dpp v228, v48, v192 row_shl:15 row_mask:0xf bank_mask:0xf
	v_fmac_f32_dpp v229, v49, v193 row_shl:15 row_mask:0xf bank_mask:0xf
	v_fmac_f32_dpp v230, v50, v194 row_shl:15 row_mask:0xf bank_mask:0xf
	v_fmac_f32_dpp v231, v51, v195 row_shl:15 row_mask:0xf bank_mask:0xf
	v_fmac_f32_dpp v228, v40, v200 row_shl:1 row_mask:0xf bank_mask:0xf
	v_fmac_f32_dpp v229, v41, v201 row_shl:1 row_mask:0xf bank_mask:0xf
	v_fmac_f32_dpp v230, v42, v202 row_shl:1 row_mask:0xf bank_mask:0xf
	v_fmac_f32_dpp v231, v43, v203 row_shl:1 row_mask:0xf bank_mask:0xf
	v_fmac_f32_dpp v228, v32, v200 row_shr:15 row_mask:0xf bank_mask:0xf
	v_fmac_f32_dpp v229, v33, v201 row_shr:15 row_mask:0xf bank_mask:0xf
	v_fmac_f32_dpp v230, v34, v202 row_shr:15 row_mask:0xf bank_mask:0xf
	v_fmac_f32_dpp v231, v35, v203 row_shr:15 row_mask:0xf bank_mask:0xf
	v_pk_mul_f32 v[232:233], v[224:225], v[238:239]
	v_pk_mul_f32 v[234:235], v[226:227], v[238:239]
	v_exp_f32_e32 v232, v232
	v_exp_f32_e32 v233, v233
	v_exp_f32_e32 v234, v234
	v_exp_f32_e32 v235, v235
	v_pk_add_f32 v[232:233], v[232:233], 1.0 op_sel_hi:[1,0]
	v_pk_add_f32 v[234:235], v[234:235], 1.0 op_sel_hi:[1,0]
	v_rcp_f32_e32 v232, v232
	v_rcp_f32_e32 v233, v233
	v_rcp_f32_e32 v234, v234
	v_rcp_f32_e32 v235, v235
	v_pk_mul_f32 v[224:225], v[224:225], v[232:233]
	v_pk_mul_f32 v[226:227], v[226:227], v[234:235]
	v_pk_mul_f32 v[224:225], v[224:225], v[228:229]
	v_pk_mul_f32 v[226:227], v[226:227], v[230:231]
	v_cvt_pk_bf16_f32 v246, v224, v225
	v_cvt_pk_bf16_f32 v247, v226, v227
	v_add_u32_e32 v213, 0x2c000, v210
	global_store_dwordx4 v213, v[244:247], s[36:37]
	v_pk_fma_f32 v[224:225], v[116:117], v[100:101], v[124:125]
	v_pk_fma_f32 v[226:227], v[118:119], v[102:103], v[126:127]
	v_fmac_f32_dpp v224, v100, v112 row_shr:1 row_mask:0xf bank_mask:0xf
	v_fmac_f32_dpp v225, v101, v113 row_shr:1 row_mask:0xf bank_mask:0xf
	v_fmac_f32_dpp v226, v102, v114 row_shr:1 row_mask:0xf bank_mask:0xf
	v_fmac_f32_dpp v227, v103, v115 row_shr:1 row_mask:0xf bank_mask:0xf
	v_fmac_f32_dpp v224, v108, v112 row_shl:15 row_mask:0xf bank_mask:0xf
	v_fmac_f32_dpp v225, v109, v113 row_shl:15 row_mask:0xf bank_mask:0xf
	v_fmac_f32_dpp v226, v110, v114 row_shl:15 row_mask:0xf bank_mask:0xf
	v_fmac_f32_dpp v227, v111, v115 row_shl:15 row_mask:0xf bank_mask:0xf
	v_fmac_f32_dpp v224, v100, v120 row_shl:1 row_mask:0xf bank_mask:0xf
	v_fmac_f32_dpp v225, v101, v121 row_shl:1 row_mask:0xf bank_mask:0xf
	v_fmac_f32_dpp v226, v102, v122 row_shl:1 row_mask:0xf bank_mask:0xf
	v_fmac_f32_dpp v227, v103, v123 row_shl:1 row_mask:0xf bank_mask:0xf
	v_pk_fma_f32 v[228:229], v[136:137], v[96:97], v[144:145]
	v_pk_fma_f32 v[230:231], v[138:139], v[98:99], v[146:147]
	v_fmac_f32_dpp v228, v96, v132 row_shr:1 row_mask:0xf bank_mask:0xf
	v_fmac_f32_dpp v229, v97, v133 row_shr:1 row_mask:0xf bank_mask:0xf
	v_fmac_f32_dpp v230, v98, v134 row_shr:1 row_mask:0xf bank_mask:0xf
	v_fmac_f32_dpp v231, v99, v135 row_shr:1 row_mask:0xf bank_mask:0xf
	v_fmac_f32_dpp v228, v104, v132 row_shl:15 row_mask:0xf bank_mask:0xf
	v_fmac_f32_dpp v229, v105, v133 row_shl:15 row_mask:0xf bank_mask:0xf
	v_fmac_f32_dpp v230, v106, v134 row_shl:15 row_mask:0xf bank_mask:0xf
	v_fmac_f32_dpp v231, v107, v135 row_shl:15 row_mask:0xf bank_mask:0xf
	v_fmac_f32_dpp v228, v96, v140 row_shl:1 row_mask:0xf bank_mask:0xf
	v_fmac_f32_dpp v229, v97, v141 row_shl:1 row_mask:0xf bank_mask:0xf
	v_fmac_f32_dpp v230, v98, v142 row_shl:1 row_mask:0xf bank_mask:0xf
	v_fmac_f32_dpp v231, v99, v143 row_shl:1 row_mask:0xf bank_mask:0xf
	v_pk_mul_f32 v[232:233], v[224:225], v[238:239]
	v_pk_mul_f32 v[234:235], v[226:227], v[238:239]
	v_exp_f32_e32 v232, v232
	v_exp_f32_e32 v233, v233
	v_exp_f32_e32 v234, v234
	v_exp_f32_e32 v235, v235
	v_pk_add_f32 v[232:233], v[232:233], 1.0 op_sel_hi:[1,0]
	v_pk_add_f32 v[234:235], v[234:235], 1.0 op_sel_hi:[1,0]
	v_rcp_f32_e32 v232, v232
	v_rcp_f32_e32 v233, v233
	v_rcp_f32_e32 v234, v234
	v_rcp_f32_e32 v235, v235
	v_pk_mul_f32 v[224:225], v[224:225], v[232:233]
	v_pk_mul_f32 v[226:227], v[226:227], v[234:235]
	v_pk_mul_f32 v[224:225], v[224:225], v[228:229]
	v_pk_mul_f32 v[226:227], v[226:227], v[230:231]
	v_cvt_pk_bf16_f32 v244, v224, v225
	v_cvt_pk_bf16_f32 v245, v226, v227
	v_pk_fma_f32 v[224:225], v[180:181], v[36:37], v[188:189]
	v_pk_fma_f32 v[226:227], v[182:183], v[38:39], v[190:191]
	v_fmac_f32_dpp v224, v36, v176 row_shr:1 row_mask:0xf bank_mask:0xf
	v_fmac_f32_dpp v225, v37, v177 row_shr:1 row_mask:0xf bank_mask:0xf
	v_fmac_f32_dpp v226, v38, v178 row_shr:1 row_mask:0xf bank_mask:0xf
	v_fmac_f32_dpp v227, v39, v179 row_shr:1 row_mask:0xf bank_mask:0xf
	v_fmac_f32_dpp v224, v44, v176 row_shl:15 row_mask:0xf bank_mask:0xf
	v_fmac_f32_dpp v225, v45, v177 row_shl:15 row_mask:0xf bank_mask:0xf
	v_fmac_f32_dpp v226, v46, v178 row_shl:15 row_mask:0xf bank_mask:0xf
	v_fmac_f32_dpp v227, v47, v179 row_shl:15 row_mask:0xf bank_mask:0xf
	v_fmac_f32_dpp v224, v36, v184 row_shl:1 row_mask:0xf bank_mask:0xf
	v_fmac_f32_dpp v225, v37, v185 row_shl:1 row_mask:0xf bank_mask:0xf
	v_fmac_f32_dpp v226, v38, v186 row_shl:1 row_mask:0xf bank_mask:0xf
	v_fmac_f32_dpp v227, v39, v187 row_shl:1 row_mask:0xf bank_mask:0xf
	v_pk_fma_f32 v[228:229], v[196:197], v[32:33], v[204:205]
	v_pk_fma_f32 v[230:231], v[198:199], v[34:35], v[206:207]
	v_fmac_f32_dpp v228, v32, v192 row_shr:1 row_mask:0xf bank_mask:0xf
	v_fmac_f32_dpp v229, v33, v193 row_shr:1 row_mask:0xf bank_mask:0xf
	v_fmac_f32_dpp v230, v34, v194 row_shr:1 row_mask:0xf bank_mask:0xf
	v_fmac_f32_dpp v231, v35, v195 row_shr:1 row_mask:0xf bank_mask:0xf
	v_fmac_f32_dpp v228, v40, v192 row_shl:15 row_mask:0xf bank_mask:0xf
	v_fmac_f32_dpp v229, v41, v193 row_shl:15 row_mask:0xf bank_mask:0xf
	v_fmac_f32_dpp v230, v42, v194 row_shl:15 row_mask:0xf bank_mask:0xf
	v_fmac_f32_dpp v231, v43, v195 row_shl:15 row_mask:0xf bank_mask:0xf
	v_fmac_f32_dpp v228, v32, v200 row_shl:1 row_mask:0xf bank_mask:0xf
	v_fmac_f32_dpp v229, v33, v201 row_shl:1 row_mask:0xf bank_mask:0xf
	v_fmac_f32_dpp v230, v34, v202 row_shl:1 row_mask:0xf bank_mask:0xf
	v_fmac_f32_dpp v231, v35, v203 row_shl:1 row_mask:0xf bank_mask:0xf
	v_pk_mul_f32 v[232:233], v[224:225], v[238:239]
	v_pk_mul_f32 v[234:235], v[226:227], v[238:239]
	v_exp_f32_e32 v232, v232
	v_exp_f32_e32 v233, v233
	v_exp_f32_e32 v234, v234
	v_exp_f32_e32 v235, v235
	v_pk_add_f32 v[232:233], v[232:233], 1.0 op_sel_hi:[1,0]
	v_pk_add_f32 v[234:235], v[234:235], 1.0 op_sel_hi:[1,0]
	v_rcp_f32_e32 v232, v232
	v_rcp_f32_e32 v233, v233
	v_rcp_f32_e32 v234, v234
	v_rcp_f32_e32 v235, v235
	v_pk_mul_f32 v[224:225], v[224:225], v[232:233]
	v_pk_mul_f32 v[226:227], v[226:227], v[234:235]
	v_pk_mul_f32 v[224:225], v[224:225], v[228:229]
	v_pk_mul_f32 v[226:227], v[226:227], v[230:231]
	v_cvt_pk_bf16_f32 v246, v224, v225
	v_cvt_pk_bf16_f32 v247, v226, v227
	v_add_u32_e32 v213, 0x42000, v210
	global_store_dwordx4 v213, v[244:247], s[36:37]
	v_pk_fma_f32 v[224:225], v[116:117], v[92:93], v[124:125]
	v_pk_fma_f32 v[226:227], v[118:119], v[94:95], v[126:127]
	v_fmac_f32_dpp v224, v92, v112 row_shr:1 row_mask:0xf bank_mask:0xf
	v_fmac_f32_dpp v225, v93, v113 row_shr:1 row_mask:0xf bank_mask:0xf
	v_fmac_f32_dpp v226, v94, v114 row_shr:1 row_mask:0xf bank_mask:0xf
	v_fmac_f32_dpp v227, v95, v115 row_shr:1 row_mask:0xf bank_mask:0xf
	v_fmac_f32_dpp v224, v92, v120 row_shl:1 row_mask:0xf bank_mask:0xf
	v_fmac_f32_dpp v225, v93, v121 row_shl:1 row_mask:0xf bank_mask:0xf
	v_fmac_f32_dpp v226, v94, v122 row_shl:1 row_mask:0xf bank_mask:0xf
	v_fmac_f32_dpp v227, v95, v123 row_shl:1 row_mask:0xf bank_mask:0xf
	v_fmac_f32_dpp v224, v84, v120 row_shr:15 row_mask:0xf bank_mask:0xf
	v_fmac_f32_dpp v225, v85, v121 row_shr:15 row_mask:0xf bank_mask:0xf
	v_fmac_f32_dpp v226, v86, v122 row_shr:15 row_mask:0xf bank_mask:0xf
	v_fmac_f32_dpp v227, v87, v123 row_shr:15 row_mask:0xf bank_mask:0xf
	v_pk_fma_f32 v[228:229], v[136:137], v[88:89], v[144:145]
	v_pk_fma_f32 v[230:231], v[138:139], v[90:91], v[146:147]
	v_fmac_f32_dpp v228, v88, v132 row_shr:1 row_mask:0xf bank_mask:0xf
	v_fmac_f32_dpp v229, v89, v133 row_shr:1 row_mask:0xf bank_mask:0xf
	v_fmac_f32_dpp v230, v90, v134 row_shr:1 row_mask:0xf bank_mask:0xf
	v_fmac_f32_dpp v231, v91, v135 row_shr:1 row_mask:0xf bank_mask:0xf
	v_fmac_f32_dpp v228, v88, v140 row_shl:1 row_mask:0xf bank_mask:0xf
	v_fmac_f32_dpp v229, v89, v141 row_shl:1 row_mask:0xf bank_mask:0xf
	v_fmac_f32_dpp v230, v90, v142 row_shl:1 row_mask:0xf bank_mask:0xf
	v_fmac_f32_dpp v231, v91, v143 row_shl:1 row_mask:0xf bank_mask:0xf
	v_fmac_f32_dpp v228, v80, v140 row_shr:15 row_mask:0xf bank_mask:0xf
	v_fmac_f32_dpp v229, v81, v141 row_shr:15 row_mask:0xf bank_mask:0xf
	v_fmac_f32_dpp v230, v82, v142 row_shr:15 row_mask:0xf bank_mask:0xf
	v_fmac_f32_dpp v231, v83, v143 row_shr:15 row_mask:0xf bank_mask:0xf
	v_pk_mul_f32 v[232:233], v[224:225], v[238:239]
	v_pk_mul_f32 v[234:235], v[226:227], v[238:239]
	v_exp_f32_e32 v232, v232
	v_exp_f32_e32 v233, v233
	v_exp_f32_e32 v234, v234
	v_exp_f32_e32 v235, v235
	v_pk_add_f32 v[232:233], v[232:233], 1.0 op_sel_hi:[1,0]
	v_pk_add_f32 v[234:235], v[234:235], 1.0 op_sel_hi:[1,0]
	v_rcp_f32_e32 v232, v232
	v_rcp_f32_e32 v233, v233
	v_rcp_f32_e32 v234, v234
	v_rcp_f32_e32 v235, v235
	v_pk_mul_f32 v[224:225], v[224:225], v[232:233]
	v_pk_mul_f32 v[226:227], v[226:227], v[234:235]
	v_pk_mul_f32 v[224:225], v[224:225], v[228:229]
	v_pk_mul_f32 v[226:227], v[226:227], v[230:231]
	v_cvt_pk_bf16_f32 v244, v224, v225
	v_cvt_pk_bf16_f32 v245, v226, v227
	v_pk_fma_f32 v[224:225], v[180:181], v[28:29], v[188:189]
	v_pk_fma_f32 v[226:227], v[182:183], v[30:31], v[190:191]
	v_fmac_f32_dpp v224, v28, v176 row_shr:1 row_mask:0xf bank_mask:0xf
	v_fmac_f32_dpp v225, v29, v177 row_shr:1 row_mask:0xf bank_mask:0xf
	v_fmac_f32_dpp v226, v30, v178 row_shr:1 row_mask:0xf bank_mask:0xf
	v_fmac_f32_dpp v227, v31, v179 row_shr:1 row_mask:0xf bank_mask:0xf
	v_fmac_f32_dpp v224, v28, v184 row_shl:1 row_mask:0xf bank_mask:0xf
	v_fmac_f32_dpp v225, v29, v185 row_shl:1 row_mask:0xf bank_mask:0xf
	v_fmac_f32_dpp v226, v30, v186 row_shl:1 row_mask:0xf bank_mask:0xf
	v_fmac_f32_dpp v227, v31, v187 row_shl:1 row_mask:0xf bank_mask:0xf
	v_fmac_f32_dpp v224, v20, v184 row_shr:15 row_mask:0xf bank_mask:0xf
	v_fmac_f32_dpp v225, v21, v185 row_shr:15 row_mask:0xf bank_mask:0xf
	v_fmac_f32_dpp v226, v22, v186 row_shr:15 row_mask:0xf bank_mask:0xf
	v_fmac_f32_dpp v227, v23, v187 row_shr:15 row_mask:0xf bank_mask:0xf
	v_pk_fma_f32 v[228:229], v[196:197], v[24:25], v[204:205]
	v_pk_fma_f32 v[230:231], v[198:199], v[26:27], v[206:207]
	v_fmac_f32_dpp v228, v24, v192 row_shr:1 row_mask:0xf bank_mask:0xf
	v_fmac_f32_dpp v229, v25, v193 row_shr:1 row_mask:0xf bank_mask:0xf
	v_fmac_f32_dpp v230, v26, v194 row_shr:1 row_mask:0xf bank_mask:0xf
	v_fmac_f32_dpp v231, v27, v195 row_shr:1 row_mask:0xf bank_mask:0xf
	v_fmac_f32_dpp v228, v24, v200 row_shl:1 row_mask:0xf bank_mask:0xf
	v_fmac_f32_dpp v229, v25, v201 row_shl:1 row_mask:0xf bank_mask:0xf
	v_fmac_f32_dpp v230, v26, v202 row_shl:1 row_mask:0xf bank_mask:0xf
	v_fmac_f32_dpp v231, v27, v203 row_shl:1 row_mask:0xf bank_mask:0xf
	v_fmac_f32_dpp v228, v16, v200 row_shr:15 row_mask:0xf bank_mask:0xf
	v_fmac_f32_dpp v229, v17, v201 row_shr:15 row_mask:0xf bank_mask:0xf
	v_fmac_f32_dpp v230, v18, v202 row_shr:15 row_mask:0xf bank_mask:0xf
	v_fmac_f32_dpp v231, v19, v203 row_shr:15 row_mask:0xf bank_mask:0xf
	v_pk_mul_f32 v[232:233], v[224:225], v[238:239]
	v_pk_mul_f32 v[234:235], v[226:227], v[238:239]
	v_exp_f32_e32 v232, v232
	v_exp_f32_e32 v233, v233
	v_exp_f32_e32 v234, v234
	v_exp_f32_e32 v235, v235
	v_pk_add_f32 v[232:233], v[232:233], 1.0 op_sel_hi:[1,0]
	v_pk_add_f32 v[234:235], v[234:235], 1.0 op_sel_hi:[1,0]
	v_rcp_f32_e32 v232, v232
	v_rcp_f32_e32 v233, v233
	v_rcp_f32_e32 v234, v234
	v_rcp_f32_e32 v235, v235
	v_pk_mul_f32 v[224:225], v[224:225], v[232:233]
	v_pk_mul_f32 v[226:227], v[226:227], v[234:235]
	v_pk_mul_f32 v[224:225], v[224:225], v[228:229]
	v_pk_mul_f32 v[226:227], v[226:227], v[230:231]
	v_cvt_pk_bf16_f32 v246, v224, v225
	v_cvt_pk_bf16_f32 v247, v226, v227
	v_add_u32_e32 v213, 0xb0000, v210
	global_store_dwordx4 v213, v[244:247], s[36:37]
	v_pk_fma_f32 v[224:225], v[116:117], v[84:85], v[124:125]
	v_pk_fma_f32 v[226:227], v[118:119], v[86:87], v[126:127]
	v_fmac_f32_dpp v224, v84, v112 row_shr:1 row_mask:0xf bank_mask:0xf
	v_fmac_f32_dpp v225, v85, v113 row_shr:1 row_mask:0xf bank_mask:0xf
	v_fmac_f32_dpp v226, v86, v114 row_shr:1 row_mask:0xf bank_mask:0xf
	v_fmac_f32_dpp v227, v87, v115 row_shr:1 row_mask:0xf bank_mask:0xf
	v_fmac_f32_dpp v224, v92, v112 row_shl:15 row_mask:0xf bank_mask:0xf
	v_fmac_f32_dpp v225, v93, v113 row_shl:15 row_mask:0xf bank_mask:0xf
	v_fmac_f32_dpp v226, v94, v114 row_shl:15 row_mask:0xf bank_mask:0xf
	v_fmac_f32_dpp v227, v95, v115 row_shl:15 row_mask:0xf bank_mask:0xf
	v_fmac_f32_dpp v224, v84, v120 row_shl:1 row_mask:0xf bank_mask:0xf
	v_fmac_f32_dpp v225, v85, v121 row_shl:1 row_mask:0xf bank_mask:0xf
	v_fmac_f32_dpp v226, v86, v122 row_shl:1 row_mask:0xf bank_mask:0xf
	v_fmac_f32_dpp v227, v87, v123 row_shl:1 row_mask:0xf bank_mask:0xf
	v_fmac_f32_dpp v224, v76, v120 row_shr:15 row_mask:0xf bank_mask:0xf
	v_fmac_f32_dpp v225, v77, v121 row_shr:15 row_mask:0xf bank_mask:0xf
	v_fmac_f32_dpp v226, v78, v122 row_shr:15 row_mask:0xf bank_mask:0xf
	v_fmac_f32_dpp v227, v79, v123 row_shr:15 row_mask:0xf bank_mask:0xf
	v_pk_fma_f32 v[228:229], v[136:137], v[80:81], v[144:145]
	v_pk_fma_f32 v[230:231], v[138:139], v[82:83], v[146:147]
	v_fmac_f32_dpp v228, v80, v132 row_shr:1 row_mask:0xf bank_mask:0xf
	v_fmac_f32_dpp v229, v81, v133 row_shr:1 row_mask:0xf bank_mask:0xf
	v_fmac_f32_dpp v230, v82, v134 row_shr:1 row_mask:0xf bank_mask:0xf
	v_fmac_f32_dpp v231, v83, v135 row_shr:1 row_mask:0xf bank_mask:0xf
	v_fmac_f32_dpp v228, v88, v132 row_shl:15 row_mask:0xf bank_mask:0xf
	v_fmac_f32_dpp v229, v89, v133 row_shl:15 row_mask:0xf bank_mask:0xf
	v_fmac_f32_dpp v230, v90, v134 row_shl:15 row_mask:0xf bank_mask:0xf
	v_fmac_f32_dpp v231, v91, v135 row_shl:15 row_mask:0xf bank_mask:0xf
	v_fmac_f32_dpp v228, v80, v140 row_shl:1 row_mask:0xf bank_mask:0xf
	v_fmac_f32_dpp v229, v81, v141 row_shl:1 row_mask:0xf bank_mask:0xf
	v_fmac_f32_dpp v230, v82, v142 row_shl:1 row_mask:0xf bank_mask:0xf
	v_fmac_f32_dpp v231, v83, v143 row_shl:1 row_mask:0xf bank_mask:0xf
	v_fmac_f32_dpp v228, v72, v140 row_shr:15 row_mask:0xf bank_mask:0xf
	v_fmac_f32_dpp v229, v73, v141 row_shr:15 row_mask:0xf bank_mask:0xf
	v_fmac_f32_dpp v230, v74, v142 row_shr:15 row_mask:0xf bank_mask:0xf
	v_fmac_f32_dpp v231, v75, v143 row_shr:15 row_mask:0xf bank_mask:0xf
	v_pk_mul_f32 v[232:233], v[224:225], v[238:239]
	v_pk_mul_f32 v[234:235], v[226:227], v[238:239]
	v_exp_f32_e32 v232, v232
	v_exp_f32_e32 v233, v233
	v_exp_f32_e32 v234, v234
	v_exp_f32_e32 v235, v235
	v_pk_add_f32 v[232:233], v[232:233], 1.0 op_sel_hi:[1,0]
	v_pk_add_f32 v[234:235], v[234:235], 1.0 op_sel_hi:[1,0]
	v_rcp_f32_e32 v232, v232
	v_rcp_f32_e32 v233, v233
	v_rcp_f32_e32 v234, v234
	v_rcp_f32_e32 v235, v235
	v_pk_mul_f32 v[224:225], v[224:225], v[232:233]
	v_pk_mul_f32 v[226:227], v[226:227], v[234:235]
	v_pk_mul_f32 v[224:225], v[224:225], v[228:229]
	v_pk_mul_f32 v[226:227], v[226:227], v[230:231]
	v_cvt_pk_bf16_f32 v244, v224, v225
	v_cvt_pk_bf16_f32 v245, v226, v227
	v_pk_fma_f32 v[224:225], v[180:181], v[20:21], v[188:189]
	v_pk_fma_f32 v[226:227], v[182:183], v[22:23], v[190:191]
	v_fmac_f32_dpp v224, v20, v176 row_shr:1 row_mask:0xf bank_mask:0xf
	v_fmac_f32_dpp v225, v21, v177 row_shr:1 row_mask:0xf bank_mask:0xf
	v_fmac_f32_dpp v226, v22, v178 row_shr:1 row_mask:0xf bank_mask:0xf
	v_fmac_f32_dpp v227, v23, v179 row_shr:1 row_mask:0xf bank_mask:0xf
	v_fmac_f32_dpp v224, v28, v176 row_shl:15 row_mask:0xf bank_mask:0xf
	v_fmac_f32_dpp v225, v29, v177 row_shl:15 row_mask:0xf bank_mask:0xf
	v_fmac_f32_dpp v226, v30, v178 row_shl:15 row_mask:0xf bank_mask:0xf
	v_fmac_f32_dpp v227, v31, v179 row_shl:15 row_mask:0xf bank_mask:0xf
	v_fmac_f32_dpp v224, v20, v184 row_shl:1 row_mask:0xf bank_mask:0xf
	v_fmac_f32_dpp v225, v21, v185 row_shl:1 row_mask:0xf bank_mask:0xf
	v_fmac_f32_dpp v226, v22, v186 row_shl:1 row_mask:0xf bank_mask:0xf
	v_fmac_f32_dpp v227, v23, v187 row_shl:1 row_mask:0xf bank_mask:0xf
	v_fmac_f32_dpp v224, v12, v184 row_shr:15 row_mask:0xf bank_mask:0xf
	v_fmac_f32_dpp v225, v13, v185 row_shr:15 row_mask:0xf bank_mask:0xf
	v_fmac_f32_dpp v226, v14, v186 row_shr:15 row_mask:0xf bank_mask:0xf
	v_fmac_f32_dpp v227, v15, v187 row_shr:15 row_mask:0xf bank_mask:0xf
	v_pk_fma_f32 v[228:229], v[196:197], v[16:17], v[204:205]
	v_pk_fma_f32 v[230:231], v[198:199], v[18:19], v[206:207]
	v_fmac_f32_dpp v228, v16, v192 row_shr:1 row_mask:0xf bank_mask:0xf
	v_fmac_f32_dpp v229, v17, v193 row_shr:1 row_mask:0xf bank_mask:0xf
	v_fmac_f32_dpp v230, v18, v194 row_shr:1 row_mask:0xf bank_mask:0xf
	v_fmac_f32_dpp v231, v19, v195 row_shr:1 row_mask:0xf bank_mask:0xf
	v_fmac_f32_dpp v228, v24, v192 row_shl:15 row_mask:0xf bank_mask:0xf
	v_fmac_f32_dpp v229, v25, v193 row_shl:15 row_mask:0xf bank_mask:0xf
	v_fmac_f32_dpp v230, v26, v194 row_shl:15 row_mask:0xf bank_mask:0xf
	v_fmac_f32_dpp v231, v27, v195 row_shl:15 row_mask:0xf bank_mask:0xf
	v_fmac_f32_dpp v228, v16, v200 row_shl:1 row_mask:0xf bank_mask:0xf
	v_fmac_f32_dpp v229, v17, v201 row_shl:1 row_mask:0xf bank_mask:0xf
	v_fmac_f32_dpp v230, v18, v202 row_shl:1 row_mask:0xf bank_mask:0xf
	v_fmac_f32_dpp v231, v19, v203 row_shl:1 row_mask:0xf bank_mask:0xf
	v_fmac_f32_dpp v228, v8, v200 row_shr:15 row_mask:0xf bank_mask:0xf
	v_fmac_f32_dpp v229, v9, v201 row_shr:15 row_mask:0xf bank_mask:0xf
	v_fmac_f32_dpp v230, v10, v202 row_shr:15 row_mask:0xf bank_mask:0xf
	v_fmac_f32_dpp v231, v11, v203 row_shr:15 row_mask:0xf bank_mask:0xf
	v_pk_mul_f32 v[232:233], v[224:225], v[238:239]
	v_pk_mul_f32 v[234:235], v[226:227], v[238:239]
	v_exp_f32_e32 v232, v232
	v_exp_f32_e32 v233, v233
	v_exp_f32_e32 v234, v234
	v_exp_f32_e32 v235, v235
	v_pk_add_f32 v[232:233], v[232:233], 1.0 op_sel_hi:[1,0]
	v_pk_add_f32 v[234:235], v[234:235], 1.0 op_sel_hi:[1,0]
	v_rcp_f32_e32 v232, v232
	v_rcp_f32_e32 v233, v233
	v_rcp_f32_e32 v234, v234
	v_rcp_f32_e32 v235, v235
	v_pk_mul_f32 v[224:225], v[224:225], v[232:233]
	v_pk_mul_f32 v[226:227], v[226:227], v[234:235]
	v_pk_mul_f32 v[224:225], v[224:225], v[228:229]
	v_pk_mul_f32 v[226:227], v[226:227], v[230:231]
	v_cvt_pk_bf16_f32 v246, v224, v225
	v_cvt_pk_bf16_f32 v247, v226, v227
	v_add_u32_e32 v213, 0xc6000, v210
	global_store_dwordx4 v213, v[244:247], s[36:37]
	v_pk_fma_f32 v[224:225], v[116:117], v[76:77], v[124:125]
	v_pk_fma_f32 v[226:227], v[118:119], v[78:79], v[126:127]
	v_fmac_f32_dpp v224, v76, v112 row_shr:1 row_mask:0xf bank_mask:0xf
	v_fmac_f32_dpp v225, v77, v113 row_shr:1 row_mask:0xf bank_mask:0xf
	v_fmac_f32_dpp v226, v78, v114 row_shr:1 row_mask:0xf bank_mask:0xf
	v_fmac_f32_dpp v227, v79, v115 row_shr:1 row_mask:0xf bank_mask:0xf
	v_fmac_f32_dpp v224, v84, v112 row_shl:15 row_mask:0xf bank_mask:0xf
	v_fmac_f32_dpp v225, v85, v113 row_shl:15 row_mask:0xf bank_mask:0xf
	v_fmac_f32_dpp v226, v86, v114 row_shl:15 row_mask:0xf bank_mask:0xf
	v_fmac_f32_dpp v227, v87, v115 row_shl:15 row_mask:0xf bank_mask:0xf
	v_fmac_f32_dpp v224, v76, v120 row_shl:1 row_mask:0xf bank_mask:0xf
	v_fmac_f32_dpp v225, v77, v121 row_shl:1 row_mask:0xf bank_mask:0xf
	v_fmac_f32_dpp v226, v78, v122 row_shl:1 row_mask:0xf bank_mask:0xf
	v_fmac_f32_dpp v227, v79, v123 row_shl:1 row_mask:0xf bank_mask:0xf
	v_fmac_f32_dpp v224, v68, v120 row_shr:15 row_mask:0xf bank_mask:0xf
	v_fmac_f32_dpp v225, v69, v121 row_shr:15 row_mask:0xf bank_mask:0xf
	v_fmac_f32_dpp v226, v70, v122 row_shr:15 row_mask:0xf bank_mask:0xf
	v_fmac_f32_dpp v227, v71, v123 row_shr:15 row_mask:0xf bank_mask:0xf
	v_pk_fma_f32 v[228:229], v[136:137], v[72:73], v[144:145]
	v_pk_fma_f32 v[230:231], v[138:139], v[74:75], v[146:147]
	v_fmac_f32_dpp v228, v72, v132 row_shr:1 row_mask:0xf bank_mask:0xf
	v_fmac_f32_dpp v229, v73, v133 row_shr:1 row_mask:0xf bank_mask:0xf
	v_fmac_f32_dpp v230, v74, v134 row_shr:1 row_mask:0xf bank_mask:0xf
	v_fmac_f32_dpp v231, v75, v135 row_shr:1 row_mask:0xf bank_mask:0xf
	v_fmac_f32_dpp v228, v80, v132 row_shl:15 row_mask:0xf bank_mask:0xf
	v_fmac_f32_dpp v229, v81, v133 row_shl:15 row_mask:0xf bank_mask:0xf
	v_fmac_f32_dpp v230, v82, v134 row_shl:15 row_mask:0xf bank_mask:0xf
	v_fmac_f32_dpp v231, v83, v135 row_shl:15 row_mask:0xf bank_mask:0xf
	v_fmac_f32_dpp v228, v72, v140 row_shl:1 row_mask:0xf bank_mask:0xf
	v_fmac_f32_dpp v229, v73, v141 row_shl:1 row_mask:0xf bank_mask:0xf
	v_fmac_f32_dpp v230, v74, v142 row_shl:1 row_mask:0xf bank_mask:0xf
	v_fmac_f32_dpp v231, v75, v143 row_shl:1 row_mask:0xf bank_mask:0xf
	v_fmac_f32_dpp v228, v64, v140 row_shr:15 row_mask:0xf bank_mask:0xf
	v_fmac_f32_dpp v229, v65, v141 row_shr:15 row_mask:0xf bank_mask:0xf
	v_fmac_f32_dpp v230, v66, v142 row_shr:15 row_mask:0xf bank_mask:0xf
	v_fmac_f32_dpp v231, v67, v143 row_shr:15 row_mask:0xf bank_mask:0xf
	v_pk_mul_f32 v[232:233], v[224:225], v[238:239]
	v_pk_mul_f32 v[234:235], v[226:227], v[238:239]
	v_exp_f32_e32 v232, v232
	v_exp_f32_e32 v233, v233
	v_exp_f32_e32 v234, v234
	v_exp_f32_e32 v235, v235
	v_pk_add_f32 v[232:233], v[232:233], 1.0 op_sel_hi:[1,0]
	v_pk_add_f32 v[234:235], v[234:235], 1.0 op_sel_hi:[1,0]
	v_rcp_f32_e32 v232, v232
	v_rcp_f32_e32 v233, v233
	v_rcp_f32_e32 v234, v234
	v_rcp_f32_e32 v235, v235
	v_pk_mul_f32 v[224:225], v[224:225], v[232:233]
	v_pk_mul_f32 v[226:227], v[226:227], v[234:235]
	v_pk_mul_f32 v[224:225], v[224:225], v[228:229]
	v_pk_mul_f32 v[226:227], v[226:227], v[230:231]
	v_cvt_pk_bf16_f32 v244, v224, v225
	v_cvt_pk_bf16_f32 v245, v226, v227
	v_pk_fma_f32 v[224:225], v[180:181], v[12:13], v[188:189]
	v_pk_fma_f32 v[226:227], v[182:183], v[14:15], v[190:191]
	v_fmac_f32_dpp v224, v12, v176 row_shr:1 row_mask:0xf bank_mask:0xf
	v_fmac_f32_dpp v225, v13, v177 row_shr:1 row_mask:0xf bank_mask:0xf
	v_fmac_f32_dpp v226, v14, v178 row_shr:1 row_mask:0xf bank_mask:0xf
	v_fmac_f32_dpp v227, v15, v179 row_shr:1 row_mask:0xf bank_mask:0xf
	v_fmac_f32_dpp v224, v20, v176 row_shl:15 row_mask:0xf bank_mask:0xf
	v_fmac_f32_dpp v225, v21, v177 row_shl:15 row_mask:0xf bank_mask:0xf
	v_fmac_f32_dpp v226, v22, v178 row_shl:15 row_mask:0xf bank_mask:0xf
	v_fmac_f32_dpp v227, v23, v179 row_shl:15 row_mask:0xf bank_mask:0xf
	v_fmac_f32_dpp v224, v12, v184 row_shl:1 row_mask:0xf bank_mask:0xf
	v_fmac_f32_dpp v225, v13, v185 row_shl:1 row_mask:0xf bank_mask:0xf
	v_fmac_f32_dpp v226, v14, v186 row_shl:1 row_mask:0xf bank_mask:0xf
	v_fmac_f32_dpp v227, v15, v187 row_shl:1 row_mask:0xf bank_mask:0xf
	v_fmac_f32_dpp v224, v4, v184 row_shr:15 row_mask:0xf bank_mask:0xf
	v_fmac_f32_dpp v225, v5, v185 row_shr:15 row_mask:0xf bank_mask:0xf
	v_fmac_f32_dpp v226, v6, v186 row_shr:15 row_mask:0xf bank_mask:0xf
	v_fmac_f32_dpp v227, v7, v187 row_shr:15 row_mask:0xf bank_mask:0xf
	v_pk_fma_f32 v[228:229], v[196:197], v[8:9], v[204:205]
	v_pk_fma_f32 v[230:231], v[198:199], v[10:11], v[206:207]
	v_fmac_f32_dpp v228, v8, v192 row_shr:1 row_mask:0xf bank_mask:0xf
	v_fmac_f32_dpp v229, v9, v193 row_shr:1 row_mask:0xf bank_mask:0xf
	v_fmac_f32_dpp v230, v10, v194 row_shr:1 row_mask:0xf bank_mask:0xf
	v_fmac_f32_dpp v231, v11, v195 row_shr:1 row_mask:0xf bank_mask:0xf
	v_fmac_f32_dpp v228, v16, v192 row_shl:15 row_mask:0xf bank_mask:0xf
	v_fmac_f32_dpp v229, v17, v193 row_shl:15 row_mask:0xf bank_mask:0xf
	v_fmac_f32_dpp v230, v18, v194 row_shl:15 row_mask:0xf bank_mask:0xf
	v_fmac_f32_dpp v231, v19, v195 row_shl:15 row_mask:0xf bank_mask:0xf
	v_fmac_f32_dpp v228, v8, v200 row_shl:1 row_mask:0xf bank_mask:0xf
	v_fmac_f32_dpp v229, v9, v201 row_shl:1 row_mask:0xf bank_mask:0xf
	v_fmac_f32_dpp v230, v10, v202 row_shl:1 row_mask:0xf bank_mask:0xf
	v_fmac_f32_dpp v231, v11, v203 row_shl:1 row_mask:0xf bank_mask:0xf
	v_fmac_f32_dpp v228, v0, v200 row_shr:15 row_mask:0xf bank_mask:0xf
	v_fmac_f32_dpp v229, v1, v201 row_shr:15 row_mask:0xf bank_mask:0xf
	v_fmac_f32_dpp v230, v2, v202 row_shr:15 row_mask:0xf bank_mask:0xf
	v_fmac_f32_dpp v231, v3, v203 row_shr:15 row_mask:0xf bank_mask:0xf
	v_pk_mul_f32 v[232:233], v[224:225], v[238:239]
	v_pk_mul_f32 v[234:235], v[226:227], v[238:239]
	v_exp_f32_e32 v232, v232
	v_exp_f32_e32 v233, v233
	v_exp_f32_e32 v234, v234
	v_exp_f32_e32 v235, v235
	v_pk_add_f32 v[232:233], v[232:233], 1.0 op_sel_hi:[1,0]
	v_pk_add_f32 v[234:235], v[234:235], 1.0 op_sel_hi:[1,0]
	v_rcp_f32_e32 v232, v232
	v_rcp_f32_e32 v233, v233
	v_rcp_f32_e32 v234, v234
	v_rcp_f32_e32 v235, v235
	v_pk_mul_f32 v[224:225], v[224:225], v[232:233]
	v_pk_mul_f32 v[226:227], v[226:227], v[234:235]
	v_pk_mul_f32 v[224:225], v[224:225], v[228:229]
	v_pk_mul_f32 v[226:227], v[226:227], v[230:231]
	v_cvt_pk_bf16_f32 v246, v224, v225
	v_cvt_pk_bf16_f32 v247, v226, v227
	v_add_u32_e32 v213, 0xdc000, v210
	global_store_dwordx4 v213, v[244:247], s[36:37]
	v_pk_fma_f32 v[224:225], v[116:117], v[68:69], v[124:125]
	v_pk_fma_f32 v[226:227], v[118:119], v[70:71], v[126:127]
	v_fmac_f32_dpp v224, v68, v112 row_shr:1 row_mask:0xf bank_mask:0xf
	v_fmac_f32_dpp v225, v69, v113 row_shr:1 row_mask:0xf bank_mask:0xf
	v_fmac_f32_dpp v226, v70, v114 row_shr:1 row_mask:0xf bank_mask:0xf
	v_fmac_f32_dpp v227, v71, v115 row_shr:1 row_mask:0xf bank_mask:0xf
	v_fmac_f32_dpp v224, v76, v112 row_shl:15 row_mask:0xf bank_mask:0xf
	v_fmac_f32_dpp v225, v77, v113 row_shl:15 row_mask:0xf bank_mask:0xf
	v_fmac_f32_dpp v226, v78, v114 row_shl:15 row_mask:0xf bank_mask:0xf
	v_fmac_f32_dpp v227, v79, v115 row_shl:15 row_mask:0xf bank_mask:0xf
	v_fmac_f32_dpp v224, v68, v120 row_shl:1 row_mask:0xf bank_mask:0xf
	v_fmac_f32_dpp v225, v69, v121 row_shl:1 row_mask:0xf bank_mask:0xf
	v_fmac_f32_dpp v226, v70, v122 row_shl:1 row_mask:0xf bank_mask:0xf
	v_fmac_f32_dpp v227, v71, v123 row_shl:1 row_mask:0xf bank_mask:0xf
	v_pk_fma_f32 v[228:229], v[136:137], v[64:65], v[144:145]
	v_pk_fma_f32 v[230:231], v[138:139], v[66:67], v[146:147]
	v_fmac_f32_dpp v228, v64, v132 row_shr:1 row_mask:0xf bank_mask:0xf
	v_fmac_f32_dpp v229, v65, v133 row_shr:1 row_mask:0xf bank_mask:0xf
	v_fmac_f32_dpp v230, v66, v134 row_shr:1 row_mask:0xf bank_mask:0xf
	v_fmac_f32_dpp v231, v67, v135 row_shr:1 row_mask:0xf bank_mask:0xf
	v_fmac_f32_dpp v228, v72, v132 row_shl:15 row_mask:0xf bank_mask:0xf
	v_fmac_f32_dpp v229, v73, v133 row_shl:15 row_mask:0xf bank_mask:0xf
	v_fmac_f32_dpp v230, v74, v134 row_shl:15 row_mask:0xf bank_mask:0xf
	v_fmac_f32_dpp v231, v75, v135 row_shl:15 row_mask:0xf bank_mask:0xf
	v_fmac_f32_dpp v228, v64, v140 row_shl:1 row_mask:0xf bank_mask:0xf
	v_fmac_f32_dpp v229, v65, v141 row_shl:1 row_mask:0xf bank_mask:0xf
	v_fmac_f32_dpp v230, v66, v142 row_shl:1 row_mask:0xf bank_mask:0xf
	v_fmac_f32_dpp v231, v67, v143 row_shl:1 row_mask:0xf bank_mask:0xf
	v_pk_mul_f32 v[232:233], v[224:225], v[238:239]
	v_pk_mul_f32 v[234:235], v[226:227], v[238:239]
	v_exp_f32_e32 v232, v232
	v_exp_f32_e32 v233, v233
	v_exp_f32_e32 v234, v234
	v_exp_f32_e32 v235, v235
	v_pk_add_f32 v[232:233], v[232:233], 1.0 op_sel_hi:[1,0]
	v_pk_add_f32 v[234:235], v[234:235], 1.0 op_sel_hi:[1,0]
	v_rcp_f32_e32 v232, v232
	v_rcp_f32_e32 v233, v233
	v_rcp_f32_e32 v234, v234
	v_rcp_f32_e32 v235, v235
	v_pk_mul_f32 v[224:225], v[224:225], v[232:233]
	v_pk_mul_f32 v[226:227], v[226:227], v[234:235]
	v_pk_mul_f32 v[224:225], v[224:225], v[228:229]
	v_pk_mul_f32 v[226:227], v[226:227], v[230:231]
	v_cvt_pk_bf16_f32 v244, v224, v225
	v_cvt_pk_bf16_f32 v245, v226, v227
	v_pk_fma_f32 v[224:225], v[180:181], v[4:5], v[188:189]
	v_pk_fma_f32 v[226:227], v[182:183], v[6:7], v[190:191]
	v_fmac_f32_dpp v224, v4, v176 row_shr:1 row_mask:0xf bank_mask:0xf
	v_fmac_f32_dpp v225, v5, v177 row_shr:1 row_mask:0xf bank_mask:0xf
	v_fmac_f32_dpp v226, v6, v178 row_shr:1 row_mask:0xf bank_mask:0xf
	v_fmac_f32_dpp v227, v7, v179 row_shr:1 row_mask:0xf bank_mask:0xf
	v_fmac_f32_dpp v224, v12, v176 row_shl:15 row_mask:0xf bank_mask:0xf
	v_fmac_f32_dpp v225, v13, v177 row_shl:15 row_mask:0xf bank_mask:0xf
	v_fmac_f32_dpp v226, v14, v178 row_shl:15 row_mask:0xf bank_mask:0xf
	v_fmac_f32_dpp v227, v15, v179 row_shl:15 row_mask:0xf bank_mask:0xf
	v_fmac_f32_dpp v224, v4, v184 row_shl:1 row_mask:0xf bank_mask:0xf
	v_fmac_f32_dpp v225, v5, v185 row_shl:1 row_mask:0xf bank_mask:0xf
	v_fmac_f32_dpp v226, v6, v186 row_shl:1 row_mask:0xf bank_mask:0xf
	v_fmac_f32_dpp v227, v7, v187 row_shl:1 row_mask:0xf bank_mask:0xf
	v_pk_fma_f32 v[228:229], v[196:197], v[0:1], v[204:205]
	v_pk_fma_f32 v[230:231], v[198:199], v[2:3], v[206:207]
	v_fmac_f32_dpp v228, v0, v192 row_shr:1 row_mask:0xf bank_mask:0xf
	v_fmac_f32_dpp v229, v1, v193 row_shr:1 row_mask:0xf bank_mask:0xf
	v_fmac_f32_dpp v230, v2, v194 row_shr:1 row_mask:0xf bank_mask:0xf
	v_fmac_f32_dpp v231, v3, v195 row_shr:1 row_mask:0xf bank_mask:0xf
	v_fmac_f32_dpp v228, v8, v192 row_shl:15 row_mask:0xf bank_mask:0xf
	v_fmac_f32_dpp v229, v9, v193 row_shl:15 row_mask:0xf bank_mask:0xf
	v_fmac_f32_dpp v230, v10, v194 row_shl:15 row_mask:0xf bank_mask:0xf
	v_fmac_f32_dpp v231, v11, v195 row_shl:15 row_mask:0xf bank_mask:0xf
	v_fmac_f32_dpp v228, v0, v200 row_shl:1 row_mask:0xf bank_mask:0xf
	v_fmac_f32_dpp v229, v1, v201 row_shl:1 row_mask:0xf bank_mask:0xf
	v_fmac_f32_dpp v230, v2, v202 row_shl:1 row_mask:0xf bank_mask:0xf
	v_fmac_f32_dpp v231, v3, v203 row_shl:1 row_mask:0xf bank_mask:0xf
	v_pk_mul_f32 v[232:233], v[224:225], v[238:239]
	v_pk_mul_f32 v[234:235], v[226:227], v[238:239]
	v_exp_f32_e32 v232, v232
	v_exp_f32_e32 v233, v233
	v_exp_f32_e32 v234, v234
	v_exp_f32_e32 v235, v235
	v_pk_add_f32 v[232:233], v[232:233], 1.0 op_sel_hi:[1,0]
	v_pk_add_f32 v[234:235], v[234:235], 1.0 op_sel_hi:[1,0]
	v_rcp_f32_e32 v232, v232
	v_rcp_f32_e32 v233, v233
	v_rcp_f32_e32 v234, v234
	v_rcp_f32_e32 v235, v235
	v_pk_mul_f32 v[224:225], v[224:225], v[232:233]
	v_pk_mul_f32 v[226:227], v[226:227], v[234:235]
	v_pk_mul_f32 v[224:225], v[224:225], v[228:229]
	v_pk_mul_f32 v[226:227], v[226:227], v[230:231]
	v_cvt_pk_bf16_f32 v246, v224, v225
	v_cvt_pk_bf16_f32 v247, v226, v227
	v_add_u32_e32 v213, 0xf2000, v210
	global_store_dwordx4 v213, v[244:247], s[36:37]
	s_andn2_b64 vcc, exec, s[10:11]
	s_mov_b64 s[2:3], -1
	s_cbranch_vccnz .LBB0_1180
	s_andn2_b64 vcc, exec, s[96:97]
	s_cbranch_vccnz .LBB0_1179
	s_barrier
	s_branch .LBB0_1179
